# v22 plus one static s_setprio 1 for waves 0-3 (the other half) around the mixer-B loop
# speedup vs baseline: 1.0002x; 1.0002x over previous
; __device__ __forceinline__ float half_max(float v) { auto rr = __builtin_amdgcn_permlane32_swap(__float_as_uint(v), __float_as_uint(v), false, false); return fmaxf(__uint_as_float(rr[0]), __uint_as_float(rr[1])); }
; #define SLOAD(i, k0) do { sr_[i].vs0 = *(const bf16x8*)(Vh + (size_t)((k0) + sr) * PW + sc); sr_[i].vs1 = *(const bf16x8*)(Vh + (size_t)((k0) + 32 + sr) * PW + sc); \
;     sr_[i].ks0 = *(const bf16x8*)(Kh + (size_t)((k0) + sr) * PW + sc); sr_[i].ks1 = *(const bf16x8*)(Kh + (size_t)((k0) + 32 + sr) * PW + sc); } while (0)
; #define SWRITE(b, i) do { *(LAS bf16x8*)(V_lds + (b) * SHM_V + vst0) = sr_[i].vs0; *(LAS bf16x8*)(V_lds + (b) * SHM_V + vst1) = sr_[i].vs1; const int kc = sc * 2; \
;     *(LAS bf16x8*)(K_lds + (b) * SHM_K + KSWZ(sr, kc)) = sr_[i].ks0; *(LAS bf16x8*)(K_lds + (b) * SHM_K + KSWZ(32 + sr, kc)) = sr_[i].ks1; } while (0)
; __device__ __forceinline__ void partialSM(f32x16& p0, f32x16& p1, const LAS float* tbp, int relc, float cL, float cR, float& m_reg, float& mn, float& alpha) {
;     ...
;     float pmax = p0[0];
; #pragma unroll
;     for (int r = 1; r < 16; ++r) pmax = fmaxf(pmax, p0[r]);
; #pragma unroll
;     for (int r = 0; r < 16; ++r) pmax = fmaxf(pmax, p1[r]);
;     pmax = half_max(pmax) + cb;
;     if (__builtin_expect(__all(pmax - m_reg <= 8.f), 1)) { mn = m_reg; alpha = 1.f; }
;     else { mn = fmaxf(m_reg, pmax); alpha = __builtin_amdgcn_exp2f(m_reg - mn); m_reg = mn; }
;     const float sh = mn - cb;
; #pragma unroll
;     for (int r = 0; r < 16; ++r) { p0[r] -= sh; p1[r] -= sh; }
; #pragma unroll
;     for (int r = 0; r < 16; ++r) p0[r] = __builtin_amdgcn_exp2f(p0[r]);
; }
; __device__ __forceinline__ void finishSM(f32x16& p0, f32x16& p1, float alpha, float& l_reg, bf16x8& pa0, bf16x8& pa1, bf16x8& pa2, bf16x8& pa3) {
; #pragma unroll
;     for (int r = 0; r < 16; ++r) p1[r] = __builtin_amdgcn_exp2f(p1[r]);
; __device__ __forceinline__ void unit(LAS unsigned char* lds, const bf16* __restrict__ PROJ, bf16* __restrict__ MIXED, const float* __restrict__ subln_g, float lam, int R0, int seq, int h, int qb) {
;     ...
;     SLOAD(SE, 0); asm volatile("s_waitcnt vmcnt(0)" ::: "memory"); SWRITE(0, SE); __syncthreads();
;     qkt(pA0, pA1, K_lds, qr, r32, cb0); partialSM(pA0, pA1, tbq, rc0, cL, cR, m_reg, mnA, alA);
;     SLOAD(SO, 64); if (2 < NT) SLOAD(SE, 128);
;     SWAIT(); SWRITE(1, SO); __syncthreads();
.LBB0_259:
	v_add_co_u32_e32 v38, vcc, s54, v32
	s_nop 6
	v_max_f32_e32 v58, v1, v1
	v_addc_co_u32_e32 v39, vcc, 0, v33, vcc
	v_add_co_u32_e32 v42, vcc, s55, v32
	v_max_f32_e32 v59, v0, v0
	s_nop 0
	v_addc_co_u32_e32 v43, vcc, 0, v33, vcc
	v_add_co_u32_e32 v46, vcc, s54, v34
	global_load_dwordx4 v[38:41], v[38:39], off
	s_nop 0
	global_load_dwordx4 v[42:45], v[42:43], off
	v_addc_co_u32_e32 v47, vcc, 0, v35, vcc
	v_add_co_u32_e32 v50, vcc, s55, v34
	v_max_f32_e32 v58, v59, v58
	s_nop 0
	v_addc_co_u32_e32 v51, vcc, 0, v35, vcc
	v_add_co_u32_e32 v54, vcc, s56, v34
	global_load_dwordx4 v[46:49], v[46:47], off
	s_nop 0
	global_load_dwordx4 v[50:53], v[50:51], off
	v_addc_co_u32_e32 v55, vcc, 0, v35, vcc
	v_add_co_u32_e32 v34, vcc, s57, v34
	s_and_b32 s4, s33, 0x3fffffc0
	s_nop 0
	v_addc_co_u32_e32 v35, vcc, 0, v35, vcc
	v_add_co_u32_e32 v56, vcc, s56, v32
	s_lshl_b32 s4, s4, 2
	s_nop 0
	v_addc_co_u32_e32 v57, vcc, 0, v33, vcc
	v_add_co_u32_e32 v32, vcc, s57, v32
	s_add_i32 s4, s4, 0
	s_nop 0
	v_addc_co_u32_e32 v33, vcc, 0, v33, vcc
	global_load_dwordx4 v[116:119], v[54:55], off
	global_load_dwordx4 v[112:115], v[34:35], off
	global_load_dwordx4 v[124:127], v[56:57], off
	global_load_dwordx4 v[120:123], v[32:33], off
	v_max3_f32 v32, v58, v2, v3
	v_max3_f32 v32, v32, v4, v5
	v_max3_f32 v32, v32, v6, v7
	v_max3_f32 v32, v32, v8, v9
	v_max3_f32 v32, v32, v10, v11
	v_max3_f32 v32, v32, v12, v13
	v_max3_f32 v32, v32, v14, v15
	v_max3_f32 v32, v32, v16, v17
	v_max3_f32 v32, v32, v18, v19
	v_max3_f32 v32, v32, v20, v21
	v_max3_f32 v32, v32, v22, v23
	v_max3_f32 v32, v32, v24, v25
	v_max3_f32 v32, v32, v26, v27
	v_max3_f32 v32, v32, v28, v29
	v_max3_f32 v32, v32, v30, v31
	v_mov_b32_e32 v33, v32
	s_nop 1
	v_permlane32_swap_b32_e32 v32, v33
	v_max_f32_e32 v33, v33, v33
	v_max_f32_e32 v32, v32, v32
	v_max_f32_e32 v32, v32, v33
	v_add_f32_e32 v32, v37, v32
	v_add_f32_e32 v33, 0x7149f2ca, v32
	s_lshr_b32 s90, s96, 6
	s_add_i32 s4, s4, 0x18000
	v_cmp_ge_f32_e32 vcc, s35, v33
	s_cmp_eq_u64 vcc, exec
	v_max_f32_e32 v32, 0xf149f2ca, v32
	s_cselect_b64 vcc, -1, 0
	v_cndmask_b32_e32 v148, v32, v214, vcc
	v_sub_f32_e32 v33, v148, v37
	v_sub_f32_e32 v0, v0, v33
	v_exp_f32_e32 v145, v0
	v_sub_f32_e32 v0, v1, v33
	v_exp_f32_e32 v158, v0
	v_sub_f32_e32 v0, v2, v33
	v_exp_f32_e32 v146, v0
	v_sub_f32_e32 v0, v3, v33
	v_exp_f32_e32 v159, v0
	v_sub_f32_e32 v0, v4, v33
	v_exp_f32_e32 v147, v0
	v_sub_f32_e32 v0, v5, v33
	v_exp_f32_e32 v228, v0
	v_sub_f32_e32 v0, v6, v33
	v_exp_f32_e32 v157, v0
	v_sub_f32_e32 v0, v7, v33
	v_exp_f32_e32 v231, v0
	v_sub_f32_e32 v0, v8, v33
	v_exp_f32_e32 v149, v0
	v_sub_f32_e32 v0, v9, v33
	v_exp_f32_e32 v153, v0
	v_sub_f32_e32 v0, v10, v33
	v_exp_f32_e32 v150, v0
	v_sub_f32_e32 v0, v11, v33
	v_exp_f32_e32 v154, v0
	v_sub_f32_e32 v0, v12, v33
	v_sub_f32_e32 v140, v16, v33
	v_sub_f32_e32 v16, 0xf149f2ca, v32
	v_exp_f32_e32 v151, v0
	v_sub_f32_e32 v0, v13, v33
	v_exp_f32_e32 v16, v16
	v_exp_f32_e32 v155, v0
	v_sub_f32_e32 v0, v14, v33
	v_exp_f32_e32 v152, v0
	v_sub_f32_e32 v0, v15, v33
	v_exp_f32_e32 v156, v0
	v_lshl_add_u32 v215, v169, 2, s4
	v_lshl_add_u32 v179, v171, 2, s4
	s_lshl_b64 s[4:5], s[6:7], 8
	s_waitcnt vmcnt(4)
	s_add_u32 s4, s29, s4
	v_lshlrev_b32_e32 v0, 2, v36
	v_mov_b32_e32 v14, v161
	v_mov_b32_e32 v15, v161
	s_waitcnt vmcnt(7)
	ds_write_b128 v210, v[38:41] offset:16384
	s_waitcnt vmcnt(6)
	ds_write_b128 v211, v[42:45] offset:16384
	s_waitcnt vmcnt(5)
	ds_write_b128 v212, v[46:49] offset:49152
	s_waitcnt vmcnt(4)
	ds_write_b128 v213, v[50:53] offset:49152
	v_sub_f32_e32 v141, v17, v33
	v_sub_f32_e32 v142, v18, v33
	v_sub_f32_e32 v143, v19, v33
	v_sub_f32_e32 v130, v20, v33
	v_sub_f32_e32 v131, v21, v33
	v_sub_f32_e32 v132, v22, v33
	v_sub_f32_e32 v133, v23, v33
	v_sub_f32_e32 v134, v24, v33
	v_sub_f32_e32 v135, v25, v33
	v_sub_f32_e32 v138, v26, v33
	v_sub_f32_e32 v139, v27, v33
	v_sub_f32_e32 v128, v28, v33
	v_sub_f32_e32 v129, v29, v33
	v_sub_f32_e32 v136, v30, v33
	v_sub_f32_e32 v137, v31, v33
	v_cndmask_b32_e64 v224, v16, 1.0, vcc
	s_addc_u32 s5, s28, s5
	v_sub_u32_e32 v223, v188, v0
	v_mov_b32_e32 v0, v161
	v_mov_b32_e32 v1, v161
	v_mov_b32_e32 v2, v161
	v_mov_b32_e32 v3, v161
	v_mov_b32_e32 v4, v161
	v_mov_b32_e32 v5, v161
	v_mov_b32_e32 v6, v161
	v_mov_b32_e32 v7, v161
	v_mov_b32_e32 v8, v161
	v_mov_b32_e32 v9, v161
	v_mov_b32_e32 v10, v161
	v_mov_b32_e32 v11, v161
	v_mov_b32_e32 v12, v161
	v_mov_b32_e32 v13, v161
	v_mov_b64_e32 v[62:63], v[14:15]
	v_mov_b64_e32 v[46:47], v[14:15]
	v_mov_b64_e32 v[30:31], v[14:15]
	s_mov_b32 s33, 2
	v_lshl_add_u64 v[182:183], v[166:167], 0, s[4:5]
	s_sub_i32 s6, 64, s97
	v_mov_b32_e32 v216, 0
	v_mov_b64_e32 v[60:61], v[12:13]
	v_mov_b64_e32 v[58:59], v[10:11]
	v_mov_b64_e32 v[56:57], v[8:9]
	v_mov_b64_e32 v[54:55], v[6:7]
	v_mov_b64_e32 v[52:53], v[4:5]
	v_mov_b64_e32 v[50:51], v[2:3]
	v_mov_b64_e32 v[48:49], v[0:1]
	v_mov_b64_e32 v[44:45], v[12:13]
	v_mov_b64_e32 v[42:43], v[10:11]
	v_mov_b64_e32 v[40:41], v[8:9]
	v_mov_b64_e32 v[38:39], v[6:7]
	v_mov_b64_e32 v[36:37], v[4:5]
	v_mov_b64_e32 v[34:35], v[2:3]
	v_mov_b64_e32 v[32:33], v[0:1]
	v_mov_b64_e32 v[28:29], v[12:13]
	v_mov_b64_e32 v[26:27], v[10:11]
	v_mov_b64_e32 v[24:25], v[8:9]
	v_mov_b64_e32 v[22:23], v[6:7]
	v_mov_b64_e32 v[20:21], v[4:5]
	v_mov_b64_e32 v[18:19], v[2:3]
	v_mov_b64_e32 v[16:17], v[0:1]
	s_waitcnt lgkmcnt(0)
	s_barrier
	v_mov_b32_e32 v250, v148
	v_mov_b32_e32 v251, 1.0
	v_mov_b32_e32 v232, v145
	v_mov_b32_e32 v233, v158
	v_mov_b32_e32 v234, v146
	v_mov_b32_e32 v235, v159
	v_mov_b32_e32 v236, v147
	v_mov_b32_e32 v237, v228
	v_mov_b32_e32 v238, v157
	v_mov_b32_e32 v239, v231
	v_mov_b32_e32 v240, v149
	v_mov_b32_e32 v241, v153
	v_mov_b32_e32 v242, v150
	v_mov_b32_e32 v243, v154
	v_mov_b32_e32 v244, v151
	v_mov_b32_e32 v245, v155
	v_mov_b32_e32 v246, v152
	v_mov_b32_e32 v247, v156
	v_exp_f32_e32 v144, v140
	v_exp_f32_e32 v145, v141
	v_exp_f32_e32 v146, v142
	v_exp_f32_e32 v147, v143
	v_exp_f32_e32 v148, v130
	v_exp_f32_e32 v149, v131
	v_exp_f32_e32 v150, v132
	v_exp_f32_e32 v151, v133
	v_exp_f32_e32 v152, v134
	v_exp_f32_e32 v153, v135
	v_exp_f32_e32 v154, v138
	v_exp_f32_e32 v155, v139
	v_exp_f32_e32 v156, v128
	v_exp_f32_e32 v157, v129
	v_exp_f32_e32 v158, v136
	v_exp_f32_e32 v159, v137
	s_waitcnt vmcnt(2)
	ds_write_b128 v212, v[112:115] offset:32768
	ds_write_b128 v213, v[116:119] offset:32768
	s_waitcnt lgkmcnt(0)
	s_mov_b32 s4, 0xffee0000
	s_mov_b32 s5, -1
	v_lshl_add_u64 v[112:113], v[182:183], 0, s[4:5]
	global_load_dwordx4 v[112:115], v[112:113], off offset:-2048
	s_mov_b32 s4, 0xfff40000
	v_lshl_add_u64 v[116:117], v[182:183], 0, s[4:5]
	global_load_dwordx4 v[116:119], v[116:117], off offset:-2048
	v_lshrrev_b32_e32 v254, 6, v168
	s_nop 1
	v_readfirstlane_b32 s4, v254
	s_nop 3
	s_cmp_lt_u32 s4, 4
	s_cbranch_scc0 .Lmb_noprio
	s_setprio 1
